# P9 epilogue pass 1: all 32 bf16 residual loads issued up front with counted vmcnt (on top of peel/noinv)
# baseline (speedup 1.0000x reference)
; __device__ __forceinline__ float bf_lo(unsigned w) { return __uint_as_float(w << 16); }
; __device__ __forceinline__ float bf_hi(unsigned w) { return __uint_as_float(w & 0xffff0000u); }
;     __device__ __forceinline__ void fused(f32x4 (&acc)[2][2][4][2], const Unit& u, int wr, int wc, int fr, int fq, LAS unsigned char* lds, int wid, int lane) const {
;     ...
;           for (int ai = 0; ai < 2; ++ai)
; #pragma unroll
;             for (int m = 0; m < 4; ++m) { const size_t off = (size_t)(row0 + ai * HALF + m * 16) * DM + col0;
; #pragma unroll
;                 for (int bj = 0; bj < 2; ++bj)
; #pragma unroll
;                     for (int n = 0; n < 2; ++n) { const u32x2 xw = *(const u32x2*)(x1b + off + bj * HALF + n * 16); const f32x4 xv = (f32x4){bf_lo(xw.x), bf_hi(xw.x), bf_lo(xw.y), bf_hi(xw.y)};
;                         acc[ai][bj][m][n] = xv + gv[bj][n] * acc[ai][bj][m][n]; }
;                 asm volatile("" : "+v"(acc[ai][0][m][0]), "+v"(acc[ai][0][m][1]), "+v"(acc[ai][1][m][0]), "+v"(acc[ai][1][m][1]));
;                 asm volatile("" ::: "memory"); } }
.LBB0_1125:
	s_add_u32 s0, s34, 0xd200000
	s_addc_u32 s1, s35, 0
	s_lshl_b32 s11, s45, 5
	s_lshl_b32 s10, s43, 8
	s_lshl_b32 s13, s8, 8
	s_add_i32 s12, s10, s50
	s_or_b32 s11, s13, s11
	v_and_or_b32 v144, v136, 12, s11
	v_or_b32_e32 v148, s12, v156
	s_ashr_i32 s11, s43, 3
	v_ashrrev_i32_e32 v149, 31, v148
	s_mul_hi_i32 s13, s11, 0x6000
	s_mulk_i32 s11, 0x6000
	v_ashrrev_i32_e32 v145, 31, v144
	v_lshlrev_b64 v[128:129], 11, v[148:149]
	s_add_u32 s12, s34, s11
	v_lshl_add_u64 v[128:129], s[0:1], 0, v[128:129]
	v_lshlrev_b64 v[150:151], 1, v[144:145]
	s_addc_u32 s13, s35, s13
	v_lshl_add_u64 v[146:147], v[128:129], 0, v[150:151]
	v_lshl_add_u64 v[128:129], v[144:145], 2, s[12:13]
	s_movk_i32 s11, 0x5000
	v_add_co_u32_e32 v128, vcc, s11, v128
	s_barrier
	v_addc_co_u32_e32 v129, vcc, 0, v129, vcc
	global_load_dwordx4 v[140:143], v[128:129], off
	global_load_dwordx4 v[136:139], v[128:129], off offset:64
	global_load_dwordx4 v[132:135], v[128:129], off offset:512
	s_nop 0
	global_load_dwordx4 v[128:131], v[128:129], off offset:576
	global_load_dwordx2 v[176:177], v[146:147], off
	global_load_dwordx2 v[178:179], v[146:147], off offset:32
	global_load_dwordx2 v[180:181], v[146:147], off offset:256
	global_load_dwordx2 v[182:183], v[146:147], off offset:288
	s_mov_b64 s[98:99], 0x8000
	v_lshl_add_u64 v[242:243], v[146:147], 0, s[98:99]
	global_load_dwordx2 v[184:185], v[242:243], off
	global_load_dwordx2 v[186:187], v[242:243], off offset:32
	global_load_dwordx2 v[188:189], v[242:243], off offset:256
	global_load_dwordx2 v[190:191], v[242:243], off offset:288
	s_mov_b64 s[98:99], 0x10000
	v_lshl_add_u64 v[242:243], v[146:147], 0, s[98:99]
	global_load_dwordx2 v[192:193], v[242:243], off
	global_load_dwordx2 v[194:195], v[242:243], off offset:32
	global_load_dwordx2 v[196:197], v[242:243], off offset:256
	global_load_dwordx2 v[198:199], v[242:243], off offset:288
	s_mov_b64 s[98:99], 0x18000
	v_lshl_add_u64 v[242:243], v[146:147], 0, s[98:99]
	global_load_dwordx2 v[200:201], v[242:243], off
	global_load_dwordx2 v[202:203], v[242:243], off offset:32
	global_load_dwordx2 v[204:205], v[242:243], off offset:256
	global_load_dwordx2 v[206:207], v[242:243], off offset:288
	s_mov_b64 s[98:99], 0x40000
	v_lshl_add_u64 v[242:243], v[146:147], 0, s[98:99]
	global_load_dwordx2 v[208:209], v[242:243], off
	global_load_dwordx2 v[210:211], v[242:243], off offset:32
	global_load_dwordx2 v[212:213], v[242:243], off offset:256
	global_load_dwordx2 v[214:215], v[242:243], off offset:288
	s_mov_b64 s[98:99], 0x48000
	v_lshl_add_u64 v[242:243], v[146:147], 0, s[98:99]
	global_load_dwordx2 v[216:217], v[242:243], off
	global_load_dwordx2 v[218:219], v[242:243], off offset:32
	global_load_dwordx2 v[220:221], v[242:243], off offset:256
	global_load_dwordx2 v[222:223], v[242:243], off offset:288
	s_mov_b64 s[98:99], 0x50000
	v_lshl_add_u64 v[242:243], v[146:147], 0, s[98:99]
	global_load_dwordx2 v[224:225], v[242:243], off
	global_load_dwordx2 v[226:227], v[242:243], off offset:32
	global_load_dwordx2 v[228:229], v[242:243], off offset:256
	global_load_dwordx2 v[230:231], v[242:243], off offset:288
	s_mov_b64 s[98:99], 0x58000
	v_lshl_add_u64 v[242:243], v[146:147], 0, s[98:99]
	global_load_dwordx2 v[232:233], v[242:243], off
	global_load_dwordx2 v[234:235], v[242:243], off offset:32
	global_load_dwordx2 v[236:237], v[242:243], off offset:256
	global_load_dwordx2 v[238:239], v[242:243], off offset:288
	v_or_b32_e32 v164, 16, v148
	v_ashrrev_i32_e32 v165, 31, v164
	v_lshlrev_b64 v[164:165], 11, v[164:165]
	v_lshl_add_u64 v[164:165], s[0:1], 0, v[164:165]
	v_lshl_add_u64 v[164:165], v[164:165], 0, v[150:151]
	s_waitcnt vmcnt(28)
	v_lshlrev_b32_e32 v166, 16, v176
	v_and_b32_e32 v167, 0xffff0000, v176
	v_lshlrev_b32_e32 v154, 16, v177
	v_and_b32_e32 v155, 0xffff0000, v177
	v_lshlrev_b32_e32 v168, 16, v178
	v_and_b32_e32 v169, 0xffff0000, v178
	v_lshlrev_b32_e32 v158, 16, v179
	v_and_b32_e32 v159, 0xffff0000, v179
	v_lshlrev_b32_e32 v172, 16, v180
	v_and_b32_e32 v173, 0xffff0000, v180
	v_lshlrev_b32_e32 v160, 16, v181
	v_and_b32_e32 v161, 0xffff0000, v181
	v_lshlrev_b32_e32 v174, 16, v182
	v_and_b32_e32 v175, 0xffff0000, v182
	v_lshlrev_b32_e32 v162, 16, v183
	v_and_b32_e32 v163, 0xffff0000, v183
	v_pk_fma_f32 v[120:121], v[120:121], v[140:141], v[166:167]
	v_pk_fma_f32 v[122:123], v[122:123], v[142:143], v[154:155]
	v_pk_fma_f32 v[124:125], v[124:125], v[136:137], v[168:169]
	v_pk_fma_f32 v[126:127], v[126:127], v[138:139], v[158:159]
	v_pk_fma_f32 v[116:117], v[116:117], v[132:133], v[172:173]
	v_pk_fma_f32 v[118:119], v[118:119], v[134:135], v[160:161]
	v_pk_fma_f32 v[112:113], v[112:113], v[128:129], v[174:175]
	v_pk_fma_f32 v[114:115], v[114:115], v[130:131], v[162:163]
	s_nop 0
	v_or_b32_e32 v164, 32, v148
	v_ashrrev_i32_e32 v165, 31, v164
	v_lshlrev_b64 v[164:165], 11, v[164:165]
	v_lshl_add_u64 v[164:165], s[0:1], 0, v[164:165]
	v_lshl_add_u64 v[164:165], v[164:165], 0, v[150:151]
	v_or_b32_e32 v148, 48, v148
	v_ashrrev_i32_e32 v149, 31, v148
	v_lshlrev_b64 v[148:149], 11, v[148:149]
	v_lshl_add_u64 v[148:149], s[0:1], 0, v[148:149]
	v_lshl_add_u64 v[148:149], v[148:149], 0, v[150:151]
	s_mov_b32 s0, 0x40000
	v_mul_f32_e32 v153, v125, v125
	v_mul_f32_e32 v157, v127, v127
	v_fmac_f32_e32 v153, v124, v124
	v_fmac_f32_e32 v157, v126, v126
	s_waitcnt vmcnt(24)
; __device__ __forceinline__ float bf_lo(unsigned w) { return __uint_as_float(w << 16); }
; __device__ __forceinline__ float bf_hi(unsigned w) { return __uint_as_float(w & 0xffff0000u); }
;     __device__ __forceinline__ void fused(f32x4 (&acc)[2][2][4][2], const Unit& u, int wr, int wc, int fr, int fq, LAS unsigned char* lds, int wid, int lane) const {
;     ...
;           for (int ai = 0; ai < 2; ++ai)
; #pragma unroll
;             for (int m = 0; m < 4; ++m) { const size_t off = (size_t)(row0 + ai * HALF + m * 16) * DM + col0;
; #pragma unroll
;                 for (int bj = 0; bj < 2; ++bj)
; #pragma unroll
;                     for (int n = 0; n < 2; ++n) { const u32x2 xw = *(const u32x2*)(x1b + off + bj * HALF + n * 16); const f32x4 xv = (f32x4){bf_lo(xw.x), bf_hi(xw.x), bf_lo(xw.y), bf_hi(xw.y)};
;                         acc[ai][bj][m][n] = xv + gv[bj][n] * acc[ai][bj][m][n]; }
;                 asm volatile("" : "+v"(acc[ai][0][m][0]), "+v"(acc[ai][0][m][1]), "+v"(acc[ai][1][m][0]), "+v"(acc[ai][1][m][1]));
;                 asm volatile("" ::: "memory"); } }
	v_lshlrev_b32_e32 v166, 16, v184
	v_and_b32_e32 v167, 0xffff0000, v184
	v_lshlrev_b32_e32 v154, 16, v185
	v_and_b32_e32 v155, 0xffff0000, v185
	v_lshlrev_b32_e32 v168, 16, v186
	v_and_b32_e32 v169, 0xffff0000, v186
	v_lshlrev_b32_e32 v158, 16, v187
	v_and_b32_e32 v159, 0xffff0000, v187
	v_lshlrev_b32_e32 v172, 16, v188
	v_and_b32_e32 v173, 0xffff0000, v188
	v_lshlrev_b32_e32 v160, 16, v189
	v_and_b32_e32 v161, 0xffff0000, v189
	v_lshlrev_b32_e32 v174, 16, v190
	v_and_b32_e32 v175, 0xffff0000, v190
	v_lshlrev_b32_e32 v162, 16, v191
	v_and_b32_e32 v163, 0xffff0000, v191
	v_pk_fma_f32 v[110:111], v[110:111], v[142:143], v[154:155]
	v_pk_fma_f32 v[108:109], v[108:109], v[140:141], v[166:167]
	v_pk_fma_f32 v[106:107], v[106:107], v[138:139], v[158:159]
	v_pk_fma_f32 v[104:105], v[104:105], v[136:137], v[168:169]
	v_pk_fma_f32 v[102:103], v[102:103], v[134:135], v[160:161]
	v_pk_fma_f32 v[100:101], v[100:101], v[132:133], v[172:173]
	v_pk_fma_f32 v[98:99], v[98:99], v[130:131], v[162:163]
	v_pk_fma_f32 v[96:97], v[96:97], v[128:129], v[174:175]
	s_nop 0
	s_waitcnt vmcnt(20)
	v_lshlrev_b32_e32 v150, 16, v192
	v_and_b32_e32 v151, 0xffff0000, v192
	v_lshlrev_b32_e32 v154, 16, v193
	v_and_b32_e32 v155, 0xffff0000, v193
	v_lshlrev_b32_e32 v164, 16, v194
	v_and_b32_e32 v165, 0xffff0000, v194
	v_lshlrev_b32_e32 v158, 16, v195
	v_and_b32_e32 v159, 0xffff0000, v195
	v_lshlrev_b32_e32 v166, 16, v196
	v_and_b32_e32 v167, 0xffff0000, v196
	v_lshlrev_b32_e32 v160, 16, v197
	v_and_b32_e32 v161, 0xffff0000, v197
	v_lshlrev_b32_e32 v168, 16, v198
	v_and_b32_e32 v169, 0xffff0000, v198
	v_lshlrev_b32_e32 v162, 16, v199
	v_and_b32_e32 v163, 0xffff0000, v199
	v_pk_fma_f32 v[94:95], v[94:95], v[142:143], v[154:155]
	v_pk_fma_f32 v[92:93], v[92:93], v[140:141], v[150:151]
	v_pk_fma_f32 v[90:91], v[90:91], v[138:139], v[158:159]
	v_pk_fma_f32 v[88:89], v[88:89], v[136:137], v[164:165]
	v_pk_fma_f32 v[86:87], v[86:87], v[134:135], v[160:161]
	v_pk_fma_f32 v[84:85], v[84:85], v[132:133], v[166:167]
	v_pk_fma_f32 v[82:83], v[82:83], v[130:131], v[162:163]
	v_pk_fma_f32 v[80:81], v[80:81], v[128:129], v[168:169]
	v_add_co_u32_e32 v160, vcc, s0, v146
	s_nop 0
	s_mov_b64 s[0:1], 0x40000
	v_addc_co_u32_e32 v161, vcc, 0, v147, vcc
	s_waitcnt vmcnt(16)
	v_lshlrev_b32_e32 v162, 16, v200
	v_and_b32_e32 v163, 0xffff0000, v200
	v_lshlrev_b32_e32 v150, 16, v201
	v_and_b32_e32 v151, 0xffff0000, v201
	v_lshlrev_b32_e32 v164, 16, v202
	v_and_b32_e32 v165, 0xffff0000, v202
	v_lshlrev_b32_e32 v154, 16, v203
	v_and_b32_e32 v155, 0xffff0000, v203
	v_lshlrev_b32_e32 v166, 16, v204
	v_and_b32_e32 v167, 0xffff0000, v204
	v_lshlrev_b32_e32 v158, 16, v205
	v_and_b32_e32 v159, 0xffff0000, v205
	v_lshlrev_b32_e32 v168, 16, v206
	v_and_b32_e32 v169, 0xffff0000, v206
	v_lshlrev_b32_e32 v148, 16, v207
	v_and_b32_e32 v149, 0xffff0000, v207
	v_pk_fma_f32 v[78:79], v[78:79], v[142:143], v[150:151]
	v_pk_fma_f32 v[76:77], v[76:77], v[140:141], v[162:163]
	v_pk_fma_f32 v[74:75], v[74:75], v[138:139], v[154:155]
	v_pk_fma_f32 v[72:73], v[72:73], v[136:137], v[164:165]
	v_pk_fma_f32 v[70:71], v[70:71], v[134:135], v[158:159]
	v_pk_fma_f32 v[68:69], v[68:69], v[132:133], v[166:167]
	v_pk_fma_f32 v[66:67], v[66:67], v[130:131], v[148:149]
	v_pk_fma_f32 v[64:65], v[64:65], v[128:129], v[168:169]
	v_lshl_add_u64 v[150:151], v[146:147], 0, s[0:1]
	s_nop 0
	s_mov_b32 s0, 0x48000
	v_add_co_u32_e32 v160, vcc, s0, v146
	s_mov_b64 s[0:1], 0x48000
	s_nop 0
	v_addc_co_u32_e32 v161, vcc, 0, v147, vcc
	s_waitcnt vmcnt(12)
	v_lshlrev_b32_e32 v164, 16, v210
	v_lshlrev_b32_e32 v162, 16, v208
	v_and_b32_e32 v163, 0xffff0000, v208
	v_lshlrev_b32_e32 v148, 16, v209
	v_and_b32_e32 v149, 0xffff0000, v209
	v_and_b32_e32 v165, 0xffff0000, v210
	v_lshlrev_b32_e32 v154, 16, v211
	v_and_b32_e32 v155, 0xffff0000, v211
	v_lshlrev_b32_e32 v166, 16, v212
	v_and_b32_e32 v167, 0xffff0000, v212
	v_lshlrev_b32_e32 v158, 16, v213
	v_and_b32_e32 v159, 0xffff0000, v213
	v_lshlrev_b32_e32 v168, 16, v214
	v_and_b32_e32 v169, 0xffff0000, v214
	v_lshlrev_b32_e32 v150, 16, v215
	v_and_b32_e32 v151, 0xffff0000, v215
	v_pk_fma_f32 v[62:63], v[62:63], v[142:143], v[148:149]
	v_pk_fma_f32 v[60:61], v[60:61], v[140:141], v[162:163]
	v_pk_fma_f32 v[58:59], v[58:59], v[138:139], v[154:155]
	v_pk_fma_f32 v[56:57], v[56:57], v[136:137], v[164:165]
	v_pk_fma_f32 v[54:55], v[54:55], v[134:135], v[158:159]
	v_pk_fma_f32 v[52:53], v[52:53], v[132:133], v[166:167]
	v_pk_fma_f32 v[50:51], v[50:51], v[130:131], v[150:151]
	v_pk_fma_f32 v[48:49], v[48:49], v[128:129], v[168:169]
	v_lshl_add_u64 v[150:151], v[146:147], 0, s[0:1]
	s_nop 0
	s_mov_b32 s0, 0x50000
	v_add_co_u32_e32 v160, vcc, s0, v146
	s_mov_b64 s[0:1], 0x50000
	s_nop 0
	v_addc_co_u32_e32 v161, vcc, 0, v147, vcc
	s_waitcnt vmcnt(8)
; __device__ __forceinline__ float bf_lo(unsigned w) { return __uint_as_float(w << 16); }
; __device__ __forceinline__ float bf_hi(unsigned w) { return __uint_as_float(w & 0xffff0000u); }
;     __device__ __forceinline__ void run(const f32x4 (&v)[2][2][4][2], const Unit& u, int wr, int wc, int fr, int fq, LAS unsigned char* lds, int wid, int lane) const {
;     ...
;         for (int ai = 0; ai < 2; ++ai)
; #pragma unroll
;             for (int m = 0; m < 4; ++m) { float s = 0.f;
; #pragma unroll
;                 for (int bj = 0; bj < 2; ++bj)
; #pragma unroll
;                     for (int n = 0; n < 2; ++n) { const f32x4 x = v[ai][bj][m][n]; s += (x[0] * x[0] + x[1] * x[1]) + (x[2] * x[2] + x[3] * x[3]); }
;                 s += __shfl_xor(s, 16); s += __shfl_xor(s, 32);
;                 if (fq == 0) P[(ai * HALF + wr * 64 + m * 16 + fr) * 4 + wc] = s; }
;     __device__ __forceinline__ void fused(f32x4 (&acc)[2][2][4][2], const Unit& u, int wr, int wc, int fr, int fq, LAS unsigned char* lds, int wid, int lane) const {
;     ...
;           for (int ai = 0; ai < 2; ++ai)
; #pragma unroll
;             for (int m = 0; m < 4; ++m) { const size_t off = (size_t)(row0 + ai * HALF + m * 16) * DM + col0;
; #pragma unroll
;                 for (int bj = 0; bj < 2; ++bj)
; #pragma unroll
;                     for (int n = 0; n < 2; ++n) { const u32x2 xw = *(const u32x2*)(x1b + off + bj * HALF + n * 16); const f32x4 xv = (f32x4){bf_lo(xw.x), bf_hi(xw.x), bf_lo(xw.y), bf_hi(xw.y)};
;                         acc[ai][bj][m][n] = xv + gv[bj][n] * acc[ai][bj][m][n]; }
;                 asm volatile("" : "+v"(acc[ai][0][m][0]), "+v"(acc[ai][0][m][1]), "+v"(acc[ai][1][m][0]), "+v"(acc[ai][1][m][1]));
;                 asm volatile("" ::: "memory"); } }
	v_lshlrev_b32_e32 v164, 16, v218
	v_lshlrev_b32_e32 v162, 16, v216
	v_and_b32_e32 v163, 0xffff0000, v216
	v_lshlrev_b32_e32 v148, 16, v217
	v_and_b32_e32 v149, 0xffff0000, v217
	v_and_b32_e32 v165, 0xffff0000, v218
	v_lshlrev_b32_e32 v154, 16, v219
	v_and_b32_e32 v155, 0xffff0000, v219
	v_lshlrev_b32_e32 v166, 16, v220
	v_and_b32_e32 v167, 0xffff0000, v220
	v_lshlrev_b32_e32 v158, 16, v221
	v_and_b32_e32 v159, 0xffff0000, v221
	v_lshlrev_b32_e32 v168, 16, v222
	v_and_b32_e32 v169, 0xffff0000, v222
	v_lshlrev_b32_e32 v150, 16, v223
	v_and_b32_e32 v151, 0xffff0000, v223
	v_pk_fma_f32 v[46:47], v[46:47], v[142:143], v[148:149]
	v_pk_fma_f32 v[44:45], v[44:45], v[140:141], v[162:163]
	v_pk_fma_f32 v[42:43], v[42:43], v[138:139], v[154:155]
	v_pk_fma_f32 v[40:41], v[40:41], v[136:137], v[164:165]
	v_pk_fma_f32 v[38:39], v[38:39], v[134:135], v[158:159]
	v_pk_fma_f32 v[36:37], v[36:37], v[132:133], v[166:167]
	v_pk_fma_f32 v[34:35], v[34:35], v[130:131], v[150:151]
	v_pk_fma_f32 v[32:33], v[32:33], v[128:129], v[168:169]
	v_lshl_add_u64 v[150:151], v[146:147], 0, s[0:1]
	s_nop 0
	s_mov_b32 s0, 0x58000
	v_add_co_u32_e32 v160, vcc, s0, v146
	s_mov_b64 s[0:1], 0x58000
	s_nop 0
	v_addc_co_u32_e32 v161, vcc, 0, v147, vcc
	v_lshl_add_u64 v[146:147], v[146:147], 0, s[0:1]
	s_lshl_b32 s0, s45, 2
	s_add_i32 s11, s0, 0
	s_waitcnt vmcnt(4)
	v_lshlrev_b32_e32 v164, 16, v226
	v_lshlrev_b32_e32 v162, 16, v224
	v_and_b32_e32 v163, 0xffff0000, v224
	v_lshlrev_b32_e32 v148, 16, v225
	v_and_b32_e32 v149, 0xffff0000, v225
	v_and_b32_e32 v165, 0xffff0000, v226
	v_lshlrev_b32_e32 v154, 16, v227
	v_and_b32_e32 v155, 0xffff0000, v227
	v_lshlrev_b32_e32 v166, 16, v228
	v_and_b32_e32 v167, 0xffff0000, v228
	v_lshlrev_b32_e32 v158, 16, v229
	v_and_b32_e32 v159, 0xffff0000, v229
	v_lshlrev_b32_e32 v168, 16, v230
	v_and_b32_e32 v169, 0xffff0000, v230
	v_lshlrev_b32_e32 v150, 16, v231
	v_and_b32_e32 v151, 0xffff0000, v231
	v_pk_fma_f32 v[30:31], v[30:31], v[142:143], v[148:149]
	v_pk_fma_f32 v[28:29], v[28:29], v[140:141], v[162:163]
	v_pk_fma_f32 v[26:27], v[26:27], v[138:139], v[154:155]
	v_pk_fma_f32 v[24:25], v[24:25], v[136:137], v[164:165]
	v_pk_fma_f32 v[22:23], v[22:23], v[134:135], v[158:159]
	v_pk_fma_f32 v[20:21], v[20:21], v[132:133], v[166:167]
	v_pk_fma_f32 v[18:19], v[18:19], v[130:131], v[150:151]
	v_pk_fma_f32 v[16:17], v[16:17], v[128:129], v[168:169]
	v_mul_f32_e32 v150, v121, v121
	s_nop 0
	v_mbcnt_lo_u32_b32 v147, -1, 0
	v_mbcnt_hi_u32_b32 v148, -1, v147
	v_mul_f32_e32 v151, v123, v123
	v_and_b32_e32 v149, 64, v148
	v_mul_f32_e32 v164, v117, v117
	v_mul_f32_e32 v165, v119, v119
	v_fmac_f32_e32 v150, v120, v120
	v_fmac_f32_e32 v151, v122, v122
	v_xor_b32_e32 v147, 16, v148
	v_add_u32_e32 v149, 64, v149
	v_mul_f32_e32 v166, v113, v113
	v_mul_f32_e32 v167, v115, v115
	v_fmac_f32_e32 v164, v116, v116
	v_fmac_f32_e32 v165, v118, v118
	v_add_f32_e32 v150, v150, v151
	v_add_f32_e32 v151, v153, v157
	v_cmp_lt_i32_e32 vcc, v147, v149
	v_fmac_f32_e32 v166, v112, v112
	v_fmac_f32_e32 v167, v114, v114
	v_add_f32_e32 v153, v164, v165
	v_add_f32_e32 v150, v150, v151
	v_cndmask_b32_e32 v147, v148, v147, vcc
	v_add_f32_e32 v157, v166, v167
	v_add_f32_e32 v150, v153, v150
	v_lshlrev_b32_e32 v147, 2, v147
	v_add_f32_e32 v150, v157, v150
	ds_bpermute_b32 v151, v147, v150
	v_xor_b32_e32 v153, 32, v148
	v_cmp_lt_i32_e32 vcc, v153, v149
	v_and_b32_e32 v146, 63, v170
	s_waitcnt lgkmcnt(0)
	v_add_f32_e32 v149, v150, v151
	v_cndmask_b32_e32 v148, v148, v153, vcc
	v_lshlrev_b32_e32 v148, 2, v148
	ds_bpermute_b32 v150, v148, v149
	v_cmp_gt_u32_e32 vcc, 16, v146
	s_waitcnt vmcnt(2)
	v_lshlrev_b32_e32 v166, 16, v234
	v_lshlrev_b32_e32 v164, 16, v232
	v_and_b32_e32 v165, 0xffff0000, v232
	v_lshlrev_b32_e32 v154, 16, v233
	v_and_b32_e32 v155, 0xffff0000, v233
	v_and_b32_e32 v167, 0xffff0000, v234
	v_lshlrev_b32_e32 v158, 16, v235
	v_and_b32_e32 v159, 0xffff0000, v235
	s_waitcnt vmcnt(1)
	v_lshlrev_b32_e32 v168, 16, v236
	v_and_b32_e32 v169, 0xffff0000, v236
	v_lshlrev_b32_e32 v160, 16, v237
	v_and_b32_e32 v161, 0xffff0000, v237
	s_waitcnt vmcnt(0)
	v_lshlrev_b32_e32 v172, 16, v238
	v_and_b32_e32 v173, 0xffff0000, v238
	v_lshlrev_b32_e32 v162, 16, v239
	v_and_b32_e32 v163, 0xffff0000, v239
	v_pk_fma_f32 v[14:15], v[14:15], v[142:143], v[154:155]
	v_pk_fma_f32 v[12:13], v[12:13], v[140:141], v[164:165]
	v_pk_fma_f32 v[10:11], v[10:11], v[138:139], v[158:159]
	v_pk_fma_f32 v[8:9], v[8:9], v[136:137], v[166:167]
	v_pk_fma_f32 v[6:7], v[6:7], v[134:135], v[160:161]
	v_pk_fma_f32 v[4:5], v[4:5], v[132:133], v[168:169]
	v_pk_fma_f32 v[2:3], v[2:3], v[130:131], v[162:163]
	v_pk_fma_f32 v[0:1], v[0:1], v[128:129], v[172:173]
	s_nop 0
	s_and_saveexec_b64 s[0:1], vcc
	v_readlane_b32 s56, v240, 6
	v_readlane_b32 s58, v240, 8
	v_readlane_b32 s57, v240, 7
	v_readlane_b32 s59, v240, 9
	s_cbranch_execz .LBB0_1127
	s_lshl_b32 s12, s44, 10
	s_add_i32 s12, s11, s12
	v_lshl_add_u32 v128, v156, 4, s12
	s_waitcnt lgkmcnt(0)
	v_add_f32_e32 v129, v149, v150
	ds_write_b32 v128, v129
